# final-layer y epilogue: final_g loaded once instead of before each of 32 stores; diff item epilogue: 15 later subLN gamma loads issued together with counted vmcnt
# speedup vs baseline: 1.0054x; 1.0054x over previous
.LBB0_749:
	s_or_b64 exec, exec, s[20:21]
	v_cmp_gt_i32_e32 vcc, 4, v81
	s_waitcnt lgkmcnt(0)
	s_barrier
	s_and_saveexec_b64 s[20:21], vcc
	s_cbranch_execz .LBB0_739
	v_readlane_b32 s0, v254, 37
	v_lshlrev_b64 v[82:83], 11, v[178:179]
	v_readlane_b32 s1, v254, 38
	v_lshlrev_b32_e32 v81, 8, v177
	v_and_b32_e32 v81, 0xffffc000, v81
	v_lshl_add_u64 v[82:83], s[0:1], 0, v[82:83]
	v_lshl_add_u64 v[94:95], s[6:7], 1, v[82:83]
	v_add3_u32 v82, 0, v80, v81
	ds_read2st64_b32 v[102:103], v82 offset1:1
	ds_read2st64_b32 v[104:105], v82 offset0:2 offset1:3
	ds_read2st64_b32 v[118:119], v82 offset0:4 offset1:5
	ds_read2st64_b32 v[110:111], v82 offset0:6 offset1:7
	ds_read2st64_b32 v[120:121], v82 offset0:8 offset1:9
	ds_read2st64_b32 v[146:147], v82 offset0:10 offset1:11
	ds_read2st64_b32 v[148:149], v82 offset0:12 offset1:13
	ds_read2st64_b32 v[150:151], v82 offset0:14 offset1:15
	ds_read2st64_b32 v[142:143], v82 offset0:16 offset1:17
	ds_read2st64_b32 v[152:153], v82 offset0:18 offset1:19
	ds_read2st64_b32 v[138:139], v82 offset0:20 offset1:21
	ds_read2st64_b32 v[144:145], v82 offset0:22 offset1:23
	ds_read2st64_b32 v[134:135], v82 offset0:24 offset1:25
	ds_read2st64_b32 v[140:141], v82 offset0:26 offset1:27
	ds_read2st64_b32 v[130:131], v82 offset0:28 offset1:29
	ds_read2st64_b32 v[136:137], v82 offset0:30 offset1:31
	ds_read2st64_b32 v[126:127], v82 offset0:32 offset1:33
	ds_read2st64_b32 v[132:133], v82 offset0:34 offset1:35
	ds_read2st64_b32 v[122:123], v82 offset0:36 offset1:37
	ds_read2st64_b32 v[128:129], v82 offset0:38 offset1:39
	ds_read2st64_b32 v[114:115], v82 offset0:40 offset1:41
	ds_read2st64_b32 v[124:125], v82 offset0:42 offset1:43
	ds_read2st64_b32 v[108:109], v82 offset0:44 offset1:45
	ds_read2st64_b32 v[116:117], v82 offset0:46 offset1:47
	ds_read2st64_b32 v[98:99], v82 offset0:48 offset1:49
	ds_read2st64_b32 v[106:107], v82 offset0:50 offset1:51
	ds_read2st64_b32 v[90:91], v82 offset0:52 offset1:53
	ds_read2st64_b32 v[96:97], v82 offset0:54 offset1:55
	ds_read2st64_b32 v[88:89], v82 offset0:56 offset1:57
	ds_read2st64_b32 v[92:93], v82 offset0:58 offset1:59
	ds_read2st64_b32 v[80:81], v82 offset0:60 offset1:61
	v_readlane_b32 s44, v254, 43
	v_readlane_b32 s52, v254, 51
	v_readlane_b32 s53, v254, 52
	v_mov_b32_e32 v177, v112
	s_waitcnt lgkmcnt(0)
	v_pk_mul_f32 v[80:81], v[170:171], v[80:81]
	s_mov_b32 s0, 0x800000
	v_pk_fma_f32 v[80:81], v[28:29], v[84:85], v[80:81] op_sel_hi:[1,0,1] neg_lo:[0,0,1] neg_hi:[0,0,1]
	ds_read2st64_b32 v[28:29], v82 offset0:62 offset1:63
	v_pk_mul_f32 v[86:87], v[80:81], v[80:81]
	v_readlane_b32 s45, v254, 44
	v_readlane_b32 s46, v254, 45
	v_readlane_b32 s47, v254, 46
	s_waitcnt lgkmcnt(0)
	v_pk_mul_f32 v[28:29], v[170:171], v[28:29]
	v_readlane_b32 s48, v254, 47
	v_pk_fma_f32 v[82:83], v[30:31], v[84:85], v[28:29] op_sel_hi:[1,0,1] neg_lo:[0,0,1] neg_hi:[0,0,1]
	v_mov_b32_e32 v28, v192
	v_mov_b32_e32 v29, v112
	v_lshlrev_b32_e32 v28, 2, v28
	v_bitop3_b32 v85, v28, s33, v203 bitop3:0x6c
	v_lshlrev_b32_e32 v28, 11, v113
	v_lshl_add_u64 v[154:155], v[94:95], 0, v[28:29]
	v_pk_mul_f32 v[94:95], v[170:171], v[104:105]
	global_load_dwordx4 v[28:31], v174, s[52:53]
	v_pk_fma_f32 v[94:95], v[66:67], v[84:85], v[94:95] op_sel_hi:[1,0,1] neg_lo:[0,0,1] neg_hi:[0,0,1]
	v_pk_mul_f32 v[66:67], v[170:171], v[102:103]
	v_pk_mul_f32 v[156:157], v[94:95], v[94:95]
	v_pk_fma_f32 v[102:103], v[64:65], v[84:85], v[66:67] op_sel_hi:[1,0,1] neg_lo:[0,0,1] neg_hi:[0,0,1]
	v_pk_mul_f32 v[66:67], v[170:171], v[110:111]
	v_pk_mul_f32 v[158:159], v[102:103], v[102:103]
	v_pk_fma_f32 v[110:111], v[70:71], v[84:85], v[66:67] op_sel_hi:[1,0,1] neg_lo:[0,0,1] neg_hi:[0,0,1]
	v_pk_mul_f32 v[66:67], v[170:171], v[118:119]
	v_lshl_add_u64 v[64:65], v[154:155], 0, v[176:177]
	v_pk_fma_f32 v[118:119], v[68:69], v[84:85], v[66:67] op_sel_hi:[1,0,1] neg_lo:[0,0,1] neg_hi:[0,0,1]
	v_pk_mul_f32 v[66:67], v[170:171], v[146:147]
	v_pk_mul_f32 v[160:161], v[118:119], v[118:119]
	v_pk_fma_f32 v[104:105], v[74:75], v[84:85], v[66:67] op_sel_hi:[1,0,1] neg_lo:[0,0,1] neg_hi:[0,0,1]
	v_pk_mul_f32 v[66:67], v[170:171], v[120:121]
	v_pk_mul_f32 v[154:155], v[110:111], v[110:111]
	v_pk_fma_f32 v[120:121], v[72:73], v[84:85], v[66:67] op_sel_hi:[1,0,1] neg_lo:[0,0,1] neg_hi:[0,0,1]
	v_pk_mul_f32 v[66:67], v[170:171], v[150:151]
	v_pk_mul_f32 v[164:165], v[120:121], v[120:121]
	v_pk_fma_f32 v[74:75], v[78:79], v[84:85], v[66:67] op_sel_hi:[1,0,1] neg_lo:[0,0,1] neg_hi:[0,0,1]
	v_pk_mul_f32 v[66:67], v[170:171], v[148:149]
	v_pk_mul_f32 v[146:147], v[104:105], v[104:105]
	v_pk_fma_f32 v[78:79], v[76:77], v[84:85], v[66:67] op_sel_hi:[1,0,1] neg_lo:[0,0,1] neg_hi:[0,0,1]
	v_pk_mul_f32 v[66:67], v[170:171], v[152:153]
	v_pk_mul_f32 v[148:149], v[78:79], v[78:79]
	v_pk_fma_f32 v[70:71], v[50:51], v[84:85], v[66:67] op_sel_hi:[1,0,1] neg_lo:[0,0,1] neg_hi:[0,0,1]
	v_pk_mul_f32 v[50:51], v[170:171], v[142:143]
	v_pk_mul_f32 v[150:151], v[74:75], v[74:75]
	v_pk_fma_f32 v[76:77], v[48:49], v[84:85], v[50:51] op_sel_hi:[1,0,1] neg_lo:[0,0,1] neg_hi:[0,0,1]
	v_pk_mul_f32 v[48:49], v[170:171], v[144:145]
	v_pk_mul_f32 v[142:143], v[76:77], v[76:77]
	v_pk_fma_f32 v[66:67], v[54:55], v[84:85], v[48:49] op_sel_hi:[1,0,1] neg_lo:[0,0,1] neg_hi:[0,0,1]
	v_pk_mul_f32 v[48:49], v[170:171], v[138:139]
	v_pk_mul_f32 v[152:153], v[70:71], v[70:71]
	v_pk_fma_f32 v[72:73], v[52:53], v[84:85], v[48:49] op_sel_hi:[1,0,1] neg_lo:[0,0,1] neg_hi:[0,0,1]
	v_pk_mul_f32 v[48:49], v[170:171], v[140:141]
	v_pk_mul_f32 v[138:139], v[72:73], v[72:73]
	v_pk_fma_f32 v[58:59], v[58:59], v[84:85], v[48:49] op_sel_hi:[1,0,1] neg_lo:[0,0,1] neg_hi:[0,0,1]
	v_pk_mul_f32 v[48:49], v[170:171], v[134:135]
	v_pk_mul_f32 v[144:145], v[66:67], v[66:67]
	v_pk_fma_f32 v[68:69], v[56:57], v[84:85], v[48:49] op_sel_hi:[1,0,1] neg_lo:[0,0,1] neg_hi:[0,0,1]
	v_pk_mul_f32 v[48:49], v[170:171], v[136:137]
	v_pk_mul_f32 v[134:135], v[68:69], v[68:69]
	v_pk_fma_f32 v[54:55], v[62:63], v[84:85], v[48:49] op_sel_hi:[1,0,1] neg_lo:[0,0,1] neg_hi:[0,0,1]
	v_pk_mul_f32 v[48:49], v[170:171], v[130:131]
	v_pk_mul_f32 v[140:141], v[58:59], v[58:59]
	v_pk_fma_f32 v[60:61], v[60:61], v[84:85], v[48:49] op_sel_hi:[1,0,1] neg_lo:[0,0,1] neg_hi:[0,0,1]
	v_pk_mul_f32 v[48:49], v[170:171], v[132:133]
	v_pk_mul_f32 v[130:131], v[60:61], v[60:61]
	v_pk_fma_f32 v[50:51], v[34:35], v[84:85], v[48:49] op_sel_hi:[1,0,1] neg_lo:[0,0,1] neg_hi:[0,0,1]
	v_pk_mul_f32 v[34:35], v[170:171], v[126:127]
	v_pk_mul_f32 v[62:63], v[54:55], v[54:55]
	v_pk_fma_f32 v[56:57], v[32:33], v[84:85], v[34:35] op_sel_hi:[1,0,1] neg_lo:[0,0,1] neg_hi:[0,0,1]
	v_pk_mul_f32 v[32:33], v[170:171], v[128:129]
	v_pk_mul_f32 v[126:127], v[56:57], v[56:57]
	v_pk_fma_f32 v[48:49], v[38:39], v[84:85], v[32:33] op_sel_hi:[1,0,1] neg_lo:[0,0,1] neg_hi:[0,0,1]
	v_pk_mul_f32 v[32:33], v[170:171], v[122:123]
	v_pk_mul_f32 v[132:133], v[50:51], v[50:51]
	v_pk_fma_f32 v[52:53], v[36:37], v[84:85], v[32:33] op_sel_hi:[1,0,1] neg_lo:[0,0,1] neg_hi:[0,0,1]
	v_pk_mul_f32 v[32:33], v[170:171], v[124:125]
	v_pk_mul_f32 v[122:123], v[52:53], v[52:53]
	v_pk_fma_f32 v[38:39], v[42:43], v[84:85], v[32:33] op_sel_hi:[1,0,1] neg_lo:[0,0,1] neg_hi:[0,0,1]
	v_pk_mul_f32 v[32:33], v[170:171], v[114:115]
	v_pk_mul_f32 v[128:129], v[48:49], v[48:49]
	v_pk_fma_f32 v[42:43], v[40:41], v[84:85], v[32:33] op_sel_hi:[1,0,1] neg_lo:[0,0,1] neg_hi:[0,0,1]
	v_pk_mul_f32 v[32:33], v[170:171], v[116:117]
	v_pk_mul_f32 v[114:115], v[42:43], v[42:43]
	v_pk_fma_f32 v[34:35], v[46:47], v[84:85], v[32:33] op_sel_hi:[1,0,1] neg_lo:[0,0,1] neg_hi:[0,0,1]
	v_pk_mul_f32 v[32:33], v[170:171], v[108:109]
	v_pk_mul_f32 v[124:125], v[38:39], v[38:39]
	v_pk_fma_f32 v[40:41], v[44:45], v[84:85], v[32:33] op_sel_hi:[1,0,1] neg_lo:[0,0,1] neg_hi:[0,0,1]
	v_pk_mul_f32 v[32:33], v[170:171], v[106:107]
	v_pk_mul_f32 v[44:45], v[40:41], v[40:41]
	v_pk_fma_f32 v[32:33], v[18:19], v[84:85], v[32:33] op_sel_hi:[1,0,1] neg_lo:[0,0,1] neg_hi:[0,0,1]
	v_pk_mul_f32 v[18:19], v[170:171], v[98:99]
	v_pk_mul_f32 v[46:47], v[34:35], v[34:35]
	v_pk_fma_f32 v[36:37], v[16:17], v[84:85], v[18:19] op_sel_hi:[1,0,1] neg_lo:[0,0,1] neg_hi:[0,0,1]
	v_pk_mul_f32 v[16:17], v[170:171], v[96:97]
	v_pk_mul_f32 v[98:99], v[36:37], v[36:37]
	v_pk_fma_f32 v[18:19], v[22:23], v[84:85], v[16:17] op_sel_hi:[1,0,1] neg_lo:[0,0,1] neg_hi:[0,0,1]
	v_pk_mul_f32 v[16:17], v[170:171], v[90:91]
	v_pk_mul_f32 v[106:107], v[32:33], v[32:33]
	v_pk_fma_f32 v[22:23], v[20:21], v[84:85], v[16:17] op_sel_hi:[1,0,1] neg_lo:[0,0,1] neg_hi:[0,0,1]
	v_pk_mul_f32 v[16:17], v[170:171], v[92:93]
	v_pk_mul_f32 v[20:21], v[170:171], v[88:89]
	v_pk_fma_f32 v[16:17], v[26:27], v[84:85], v[16:17] op_sel_hi:[1,0,1] neg_lo:[0,0,1] neg_hi:[0,0,1]
	v_pk_fma_f32 v[20:21], v[24:25], v[84:85], v[20:21] op_sel_hi:[1,0,1] neg_lo:[0,0,1] neg_hi:[0,0,1]
	v_add_f32_e32 v84, v158, v159
	v_add_f32_e32 v84, v84, v156
	v_add_f32_e32 v84, v84, v157
	v_add_f32_e32 v84, v84, v160
	v_add_f32_e32 v84, v84, v161
	v_add_f32_e32 v84, v84, v154
	v_add_f32_e32 v84, v84, v155
	v_add_f32_e32 v84, v84, v164
	v_add_f32_e32 v84, v84, v165
	v_add_f32_e32 v84, v84, v146
	v_add_f32_e32 v84, v84, v147
	v_add_f32_e32 v84, v84, v148
	v_add_f32_e32 v84, v84, v149
	v_add_f32_e32 v84, v84, v150
	v_add_f32_e32 v84, v84, v151
	v_add_f32_e32 v84, v84, v142
	v_add_f32_e32 v84, v84, v143
	v_add_f32_e32 v84, v84, v152
	v_add_f32_e32 v84, v84, v153
	v_add_f32_e32 v84, v84, v138
	v_add_f32_e32 v84, v84, v139
	v_add_f32_e32 v84, v84, v144
	v_add_f32_e32 v84, v84, v145
	v_add_f32_e32 v84, v84, v134
	v_add_f32_e32 v84, v84, v135
	v_add_f32_e32 v84, v84, v140
	v_add_f32_e32 v84, v84, v141
	v_add_f32_e32 v84, v84, v130
	v_add_f32_e32 v84, v84, v131
	v_add_f32_e32 v62, v84, v62
	v_add_f32_e32 v62, v62, v63
	v_add_f32_e32 v62, v62, v126
	v_add_f32_e32 v62, v62, v127
	v_add_f32_e32 v62, v62, v132
	v_add_f32_e32 v62, v62, v133
	v_add_f32_e32 v62, v62, v122
	v_add_f32_e32 v62, v62, v123
	v_add_f32_e32 v62, v62, v128
	v_add_f32_e32 v62, v62, v129
	v_add_f32_e32 v62, v62, v114
	v_add_f32_e32 v62, v62, v115
	v_add_f32_e32 v62, v62, v124
	v_add_f32_e32 v62, v62, v125
	v_add_f32_e32 v44, v62, v44
	v_add_f32_e32 v44, v44, v45
	v_add_f32_e32 v44, v44, v46
	v_add_f32_e32 v44, v44, v47
	v_add_f32_e32 v44, v44, v98
	v_add_f32_e32 v44, v44, v99
	v_add_f32_e32 v44, v44, v106
	v_pk_mul_f32 v[90:91], v[22:23], v[22:23]
	v_add_f32_e32 v44, v44, v107
	v_add_f32_e32 v44, v44, v90
	v_pk_mul_f32 v[96:97], v[18:19], v[18:19]
	v_add_f32_e32 v44, v44, v91
	v_add_f32_e32 v44, v44, v96
	v_pk_mul_f32 v[24:25], v[20:21], v[20:21]
	v_add_f32_e32 v44, v44, v97
	v_add_f32_e32 v24, v44, v24
	v_pk_mul_f32 v[26:27], v[16:17], v[16:17]
	v_add_f32_e32 v24, v24, v25
	v_add_f32_e32 v24, v24, v26
	v_add_f32_e32 v24, v24, v27
	v_add_f32_e32 v24, v24, v86
	v_pk_mul_f32 v[100:101], v[82:83], v[82:83]
	v_add_f32_e32 v24, v24, v87
	v_add_f32_e32 v24, v24, v100
	v_add_f32_e32 v24, v24, v101
	ds_bpermute_b32 v25, v85, v24
	v_readlane_b32 s49, v254, 48
	v_readlane_b32 s50, v254, 49
	v_readlane_b32 s51, v254, 50
	v_readlane_b32 s54, v254, 53
	s_waitcnt lgkmcnt(0)
	v_add_f32_e32 v24, v24, v25
	v_fmamk_f32 v24, v24, 0x3c000000, v200
	v_cmp_gt_f32_e32 vcc, s0, v24
	v_mul_f32_e32 v25, 0x4b800000, v24
	v_readlane_b32 s55, v254, 54
	v_cndmask_b32_e32 v24, v24, v25, vcc
	v_rsq_f32_e32 v24, v24
	v_readlane_b32 s56, v254, 55
	v_readlane_b32 s57, v254, 56
	v_readlane_b32 s58, v254, 57
	v_mul_f32_e32 v25, 0x45800000, v24
	v_cndmask_b32_e32 v24, v24, v25, vcc
	v_mul_f32_e32 v24, 0x3f24fd5c, v24
	v_pk_mul_f32 v[26:27], v[102:103], v[24:25] op_sel_hi:[1,0]
	v_pk_mul_f32 v[22:23], v[22:23], v[24:25] op_sel_hi:[1,0]
	global_load_dwordx4 v[214:217], v174, s[52:53] offset:32
	global_load_dwordx4 v[218:221], v174, s[52:53] offset:64
	global_load_dwordx4 v[222:225], v174, s[52:53] offset:96
	global_load_dwordx4 v[226:229], v174, s[52:53] offset:128
	global_load_dwordx4 v[230:233], v174, s[52:53] offset:160
	global_load_dwordx4 v[234:237], v174, s[52:53] offset:192
	global_load_dwordx4 v[238:241], v174, s[52:53] offset:224
	global_load_dwordx4 v[242:245], v174, s[52:53] offset:256
	global_load_dwordx4 v[246:249], v174, s[52:53] offset:288
	global_load_dwordx4 v[142:145], v174, s[52:53] offset:320
	global_load_dwordx4 v[146:149], v174, s[52:53] offset:352
	global_load_dwordx4 v[150:153], v174, s[52:53] offset:384
	global_load_dwordx4 v[154:157], v174, s[52:53] offset:416
	global_load_dwordx4 v[158:161], v174, s[52:53] offset:448
	global_load_dwordx4 v[176:179], v174, s[52:53] offset:480
	s_waitcnt vmcnt(15)
	v_pk_mul_f32 v[26:27], v[28:29], v[26:27]
	v_pk_mul_f32 v[28:29], v[94:95], v[24:25] op_sel_hi:[1,0]
	v_cvt_pk_bf16_f32 v26, v26, v27
	v_pk_mul_f32 v[28:29], v[30:31], v[28:29]
	v_pk_mul_f32 v[30:31], v[118:119], v[24:25] op_sel_hi:[1,0]
	v_cvt_pk_bf16_f32 v27, v28, v29
	global_store_dwordx2 v[64:65], v[26:27], off
	v_pk_mul_f32 v[18:19], v[18:19], v[24:25] op_sel_hi:[1,0]
	v_pk_mul_f32 v[16:17], v[16:17], v[24:25] op_sel_hi:[1,0]
	v_readlane_b32 s59, v254, 58
	s_waitcnt vmcnt(15)
	v_pk_mul_f32 v[26:27], v[214:215], v[30:31]
	v_pk_mul_f32 v[30:31], v[110:111], v[24:25] op_sel_hi:[1,0]
	v_cvt_pk_bf16_f32 v26, v26, v27
	v_pk_mul_f32 v[28:29], v[216:217], v[30:31]
	v_pk_mul_f32 v[30:31], v[120:121], v[24:25] op_sel_hi:[1,0]
	v_cvt_pk_bf16_f32 v27, v28, v29
	global_store_dwordx2 v[64:65], v[26:27], off offset:16
	s_waitcnt vmcnt(15)
	v_pk_mul_f32 v[26:27], v[218:219], v[30:31]
	v_pk_mul_f32 v[30:31], v[104:105], v[24:25] op_sel_hi:[1,0]
	v_cvt_pk_bf16_f32 v26, v26, v27
	v_pk_mul_f32 v[28:29], v[220:221], v[30:31]
	v_pk_mul_f32 v[30:31], v[78:79], v[24:25] op_sel_hi:[1,0]
	v_cvt_pk_bf16_f32 v27, v28, v29
	global_store_dwordx2 v[64:65], v[26:27], off offset:32
	s_waitcnt vmcnt(15)
	v_pk_mul_f32 v[26:27], v[222:223], v[30:31]
	v_pk_mul_f32 v[30:31], v[74:75], v[24:25] op_sel_hi:[1,0]
	v_cvt_pk_bf16_f32 v26, v26, v27
	v_pk_mul_f32 v[28:29], v[224:225], v[30:31]
	v_pk_mul_f32 v[30:31], v[76:77], v[24:25] op_sel_hi:[1,0]
	v_cvt_pk_bf16_f32 v27, v28, v29
	global_store_dwordx2 v[64:65], v[26:27], off offset:48
	s_waitcnt vmcnt(15)
	v_pk_mul_f32 v[26:27], v[226:227], v[30:31]
	v_pk_mul_f32 v[30:31], v[70:71], v[24:25] op_sel_hi:[1,0]
	v_cvt_pk_bf16_f32 v26, v26, v27
	v_pk_mul_f32 v[28:29], v[228:229], v[30:31]
	v_pk_mul_f32 v[30:31], v[72:73], v[24:25] op_sel_hi:[1,0]
	v_cvt_pk_bf16_f32 v27, v28, v29
	global_store_dwordx2 v[64:65], v[26:27], off offset:64
	s_waitcnt vmcnt(15)
	v_pk_mul_f32 v[26:27], v[230:231], v[30:31]
	v_pk_mul_f32 v[30:31], v[66:67], v[24:25] op_sel_hi:[1,0]
	v_cvt_pk_bf16_f32 v26, v26, v27
	v_pk_mul_f32 v[28:29], v[232:233], v[30:31]
	v_pk_mul_f32 v[30:31], v[68:69], v[24:25] op_sel_hi:[1,0]
	v_cvt_pk_bf16_f32 v27, v28, v29
	global_store_dwordx2 v[64:65], v[26:27], off offset:80
	s_waitcnt vmcnt(15)
	v_pk_mul_f32 v[26:27], v[30:31], v[234:235]
	v_pk_mul_f32 v[30:31], v[58:59], v[24:25] op_sel_hi:[1,0]
	v_cvt_pk_bf16_f32 v26, v26, v27
	v_pk_mul_f32 v[28:29], v[30:31], v[236:237]
	v_pk_mul_f32 v[30:31], v[60:61], v[24:25] op_sel_hi:[1,0]
	v_cvt_pk_bf16_f32 v27, v28, v29
	global_store_dwordx2 v[64:65], v[26:27], off offset:96
	s_waitcnt vmcnt(15)
	v_pk_mul_f32 v[26:27], v[30:31], v[238:239]
	v_pk_mul_f32 v[30:31], v[54:55], v[24:25] op_sel_hi:[1,0]
	v_cvt_pk_bf16_f32 v26, v26, v27
	v_pk_mul_f32 v[28:29], v[30:31], v[240:241]
	v_pk_mul_f32 v[30:31], v[56:57], v[24:25] op_sel_hi:[1,0]
	v_cvt_pk_bf16_f32 v27, v28, v29
	global_store_dwordx2 v[64:65], v[26:27], off offset:112
	s_waitcnt vmcnt(15)
	v_pk_mul_f32 v[26:27], v[30:31], v[242:243]
	v_pk_mul_f32 v[30:31], v[50:51], v[24:25] op_sel_hi:[1,0]
	v_cvt_pk_bf16_f32 v26, v26, v27
	v_pk_mul_f32 v[28:29], v[30:31], v[244:245]
	v_pk_mul_f32 v[30:31], v[52:53], v[24:25] op_sel_hi:[1,0]
	v_cvt_pk_bf16_f32 v27, v28, v29
	global_store_dwordx2 v[64:65], v[26:27], off offset:128
	s_waitcnt vmcnt(15)
	v_pk_mul_f32 v[26:27], v[30:31], v[246:247]
	v_pk_mul_f32 v[30:31], v[48:49], v[24:25] op_sel_hi:[1,0]
	v_cvt_pk_bf16_f32 v26, v26, v27
	v_pk_mul_f32 v[28:29], v[30:31], v[248:249]
	v_pk_mul_f32 v[30:31], v[42:43], v[24:25] op_sel_hi:[1,0]
	v_cvt_pk_bf16_f32 v27, v28, v29
	global_store_dwordx2 v[64:65], v[26:27], off offset:144
	s_waitcnt vmcnt(15)
	v_pk_mul_f32 v[26:27], v[30:31], v[142:143]
	v_pk_mul_f32 v[30:31], v[38:39], v[24:25] op_sel_hi:[1,0]
	v_cvt_pk_bf16_f32 v26, v26, v27
	v_pk_mul_f32 v[28:29], v[30:31], v[144:145]
	v_pk_mul_f32 v[30:31], v[40:41], v[24:25] op_sel_hi:[1,0]
	v_cvt_pk_bf16_f32 v27, v28, v29
	global_store_dwordx2 v[64:65], v[26:27], off offset:160
	s_waitcnt vmcnt(15)
	v_pk_mul_f32 v[26:27], v[30:31], v[146:147]
	v_pk_mul_f32 v[30:31], v[34:35], v[24:25] op_sel_hi:[1,0]
	v_cvt_pk_bf16_f32 v26, v26, v27
	v_pk_mul_f32 v[28:29], v[30:31], v[148:149]
	v_pk_mul_f32 v[30:31], v[36:37], v[24:25] op_sel_hi:[1,0]
	v_cvt_pk_bf16_f32 v27, v28, v29
	global_store_dwordx2 v[64:65], v[26:27], off offset:176
	s_waitcnt vmcnt(15)
	v_pk_mul_f32 v[26:27], v[30:31], v[150:151]
	v_pk_mul_f32 v[30:31], v[32:33], v[24:25] op_sel_hi:[1,0]
	v_cvt_pk_bf16_f32 v26, v26, v27
	v_pk_mul_f32 v[28:29], v[30:31], v[152:153]
	s_nop 0
	v_cvt_pk_bf16_f32 v27, v28, v29
	global_store_dwordx2 v[64:65], v[26:27], off offset:192
	s_waitcnt vmcnt(15)
	v_pk_mul_f32 v[22:23], v[22:23], v[154:155]
	v_pk_mul_f32 v[18:19], v[18:19], v[156:157]
	v_cvt_pk_bf16_f32 v22, v22, v23
	v_cvt_pk_bf16_f32 v23, v18, v19
	global_store_dwordx2 v[64:65], v[22:23], off offset:208
	v_pk_mul_f32 v[18:19], v[20:21], v[24:25] op_sel_hi:[1,0]
	v_pk_mul_f32 v[20:21], v[80:81], v[24:25] op_sel_hi:[1,0]
	s_waitcnt vmcnt(15)
	v_pk_mul_f32 v[18:19], v[18:19], v[158:159]
	v_pk_mul_f32 v[16:17], v[16:17], v[160:161]
	v_cvt_pk_bf16_f32 v18, v18, v19
	v_cvt_pk_bf16_f32 v19, v16, v17
	global_store_dwordx2 v[64:65], v[18:19], off offset:224
	s_waitcnt vmcnt(15)
	v_pk_mul_f32 v[16:17], v[20:21], v[176:177]
	v_pk_mul_f32 v[20:21], v[82:83], v[24:25] op_sel_hi:[1,0]
	v_cvt_pk_bf16_f32 v16, v16, v17
	v_pk_mul_f32 v[18:19], v[20:21], v[178:179]
	s_nop 0
	v_cvt_pk_bf16_f32 v17, v18, v19
	global_store_dwordx2 v[64:65], v[16:17], off offset:240
	v_mov_b32_e32 v26, v158
	v_mov_b32_e32 v27, v159
	v_mov_b32_e32 v28, v160
	v_mov_b32_e32 v29, v161
	s_branch .LBB0_739
